# v77 + attention sink load no longer drains the K/V prefetch before the Q loads (sink lands in v255, scaled after the first counted Q wait)
# speedup vs baseline: 1.0052x; 1.0052x over previous
.LBB0_644:
	s_lshr_b32 s1, s0, 3
	s_and_b32 s1, s1, 24
	v_readlane_b32 s2, v254, 48
	s_add_i32 s6, s1, s2
	s_lshl_b32 s1, s6, 2
	v_readlane_b32 s16, v254, 2
	v_mov_b32_e32 v2, s1
	v_readlane_b32 s28, v254, 14
	v_readlane_b32 s29, v254, 15
	s_lshl_b32 s2, s0, 6
	s_and_b32 s7, s2, 0xfc0
	s_cmpk_gt_u32 s7, 0x7f
	s_cselect_b64 s[2:3], -1, 0
	s_lshl_b32 s15, s0, 4
	global_load_dword v255, v2, s[28:29]
	s_mov_b32 s1, s5
	s_sub_i32 s14, 0x80, s7
	s_lshl_b32 s4, s6, 6
	s_lshl_b32 s0, s6, 7
	s_and_b32 s6, s15, 0xfffff000
	v_readlane_b32 s18, v254, 4
	v_readlane_b32 s19, v254, 5
	s_ashr_i32 s96, s14, 5
	v_lshl_add_u64 v[212:213], v[208:209], 0, s[0:1]
	s_or_b32 s0, s6, s7
	s_mov_b32 s16, 0
	v_lshl_add_u64 v[214:215], v[210:211], 0, s[4:5]
	s_add_i32 s4, s96, -1
	s_add_i32 s97, s96, -3
	v_or_b32_e32 v127, s0, v221
	s_mov_b64 s[18:19], -1
	v_readlane_b32 s17, v254, 3
	v_readlane_b32 s20, v254, 6
	v_readlane_b32 s21, v254, 7
	v_readlane_b32 s22, v254, 8
	v_readlane_b32 s23, v254, 9
	v_readlane_b32 s24, v254, 10
	v_readlane_b32 s25, v254, 11
	v_readlane_b32 s26, v254, 12
	v_readlane_b32 s27, v254, 13
	v_readlane_b32 s30, v254, 16
	v_readlane_b32 s31, v254, 17
.LBB0_645:
	v_lshl_or_b32 v2, s16, 5, v127
	v_ashrrev_i32_e32 v3, 31, v2
	v_lshlrev_b64 v[216:217], 12, v[2:3]
	v_lshl_add_u64 v[6:7], v[212:213], 0, v[216:217]
	global_load_dwordx4 v[2:5], v[6:7], off
	global_load_dwordx4 v[132:135], v[6:7], off offset:32
	global_load_dwordx4 v[136:139], v[6:7], off offset:64
	global_load_dwordx4 v[140:143], v[6:7], off offset:96
	s_mul_i32 s7, s16, 0x1200
	s_add_i32 s6, s7, 0x1200
	s_add_i32 s15, s7, 0x2400
	v_add_u32_e32 v18, s7, v222
	v_add_u32_e32 v34, s6, v222
	v_add_u32_e32 v51, s15, v222
	s_add_i32 s14, s7, 0x3600
	ds_read_b128 v[6:9], v18
	ds_read_b128 v[10:13], v18 offset:32
	ds_read_b128 v[14:17], v18 offset:64
	ds_read_b128 v[18:21], v18 offset:96
	ds_read_b128 v[22:25], v34
	ds_read_b128 v[26:29], v34 offset:32
	ds_read_b128 v[30:33], v34 offset:64
	ds_read_b128 v[34:37], v34 offset:96
	s_or_b32 s1, s16, 2
	ds_read_b128 v[38:41], v51
	ds_read_b128 v[42:45], v51 offset:32
	ds_read_b128 v[46:49], v51 offset:64
	ds_read_b128 v[144:147], v51 offset:96
	v_add_u32_e32 v51, s14, v222
	s_or_b32 s20, s16, 4
	s_add_i32 s0, s7, 0x4800
	ds_read_b128 v[148:151], v51
	ds_read_b128 v[152:155], v51 offset:32
	ds_read_b128 v[156:159], v51 offset:64
	ds_read_b128 v[160:163], v51 offset:96
	v_add_u32_e32 v51, s0, v222
	s_cmp_le_i32 s96, s16
	v_cndmask_b32_e64 v50, 0, 1, s[18:19]
	ds_read_b128 v[180:183], v51
	ds_read_b128 v[184:187], v51 offset:32
	ds_read_b128 v[188:191], v51 offset:64
	ds_read_b128 v[192:195], v51 offset:96
	ds_read_b128 v[164:167], v222 offset:27648
	ds_read_b128 v[168:171], v222 offset:27680
	ds_read_b128 v[172:175], v222 offset:27712
	ds_read_b128 v[176:179], v222 offset:27744
	v_mov_b32_e32 v51, v224
	s_cselect_b64 s[18:19], -1, 0
	s_or_b64 s[18:19], s[2:3], s[18:19]
	v_cmp_gt_i32_e32 vcc, 0, v51
	s_and_b64 s[86:87], vcc, s[18:19]
	v_cmp_gt_i32_e32 vcc, 1, v51
	s_and_b64 s[82:83], vcc, s[18:19]
	v_cmp_gt_i32_e32 vcc, 2, v51
	s_and_b64 s[84:85], vcc, s[18:19]
	v_cmp_gt_i32_e32 vcc, 3, v51
	s_and_b64 s[78:79], vcc, s[18:19]
	v_cmp_gt_i32_e32 vcc, 8, v51
	s_and_b64 s[80:81], vcc, s[18:19]
	v_cmp_gt_i32_e32 vcc, 9, v51
	s_and_b64 s[74:75], vcc, s[18:19]
	v_cmp_gt_i32_e32 vcc, 10, v51
	s_and_b64 s[76:77], vcc, s[18:19]
	v_cmp_gt_i32_e32 vcc, 11, v51
	s_and_b64 s[70:71], vcc, s[18:19]
	v_cmp_gt_i32_e32 vcc, 16, v51
	s_and_b64 s[72:73], vcc, s[18:19]
	v_cmp_gt_i32_e32 vcc, 17, v51
	s_and_b64 s[66:67], vcc, s[18:19]
	v_cmp_gt_i32_e32 vcc, 18, v51
	s_and_b64 s[68:69], vcc, s[18:19]
	v_cmp_gt_i32_e32 vcc, 19, v51
	s_and_b64 s[62:63], vcc, s[18:19]
	v_cmp_gt_i32_e32 vcc, 24, v51
	s_and_b64 s[64:65], vcc, s[18:19]
	v_cmp_gt_i32_e32 vcc, 25, v51
	s_and_b64 s[58:59], vcc, s[18:19]
	v_cmp_gt_i32_e32 vcc, 26, v51
	s_and_b64 s[60:61], vcc, s[18:19]
	v_cmp_gt_i32_e32 vcc, 27, v51
	s_and_b64 s[56:57], vcc, s[18:19]
	s_cmp_ge_i32 s16, s4
	s_cselect_b64 s[18:19], -1, 0
	s_or_b64 s[54:55], s[2:3], s[18:19]
	s_cmp_le_i32 s96, s1
	s_cselect_b64 s[18:19], -1, 0
	s_or_b64 s[52:53], s[2:3], s[18:19]
	s_cmp_ge_i32 s16, s97
	s_cselect_b64 s[16:17], -1, 0
	s_or_b64 s[36:37], s[2:3], s[16:17]
	s_cmp_le_i32 s96, s20
	s_cselect_b64 s[16:17], -1, 0
	s_or_b64 s[16:17], s[2:3], s[16:17]
	v_cmp_lt_i32_e32 vcc, -1, v51
	s_and_b64 s[50:51], vcc, s[16:17]
	v_cmp_lt_i32_e32 vcc, 0, v51
	s_and_b64 s[46:47], vcc, s[16:17]
	v_cmp_lt_i32_e32 vcc, 1, v51
	s_and_b64 s[48:49], vcc, s[16:17]
	v_cmp_lt_i32_e32 vcc, 2, v51
	s_and_b64 s[42:43], vcc, s[16:17]
	v_cmp_lt_i32_e32 vcc, 7, v51
	s_and_b64 s[44:45], vcc, s[16:17]
	v_cmp_lt_i32_e32 vcc, 8, v51
	s_and_b64 s[38:39], vcc, s[16:17]
	v_cmp_lt_i32_e32 vcc, 9, v51
	s_and_b64 s[40:41], vcc, s[16:17]
	v_cmp_lt_i32_e32 vcc, 10, v51
	s_and_b64 s[30:31], vcc, s[16:17]
	v_cmp_lt_i32_e32 vcc, 15, v51
	s_waitcnt vmcnt(3) lgkmcnt(14)
	v_mul_f32_e32 v201, 0x3fb8aa3b, v255
	v_mfma_f32_32x32x16_bf16 v[82:97], v[6:9], v[2:5], 0
	s_and_b64 s[34:35], vcc, s[16:17]
	v_cmp_lt_i32_e32 vcc, 16, v51
	s_and_b64 s[26:27], vcc, s[16:17]
	v_cmp_lt_i32_e32 vcc, 17, v51
	s_and_b64 s[28:29], vcc, s[16:17]
	v_cmp_lt_i32_e32 vcc, 18, v51
	s_and_b64 s[22:23], vcc, s[16:17]
	v_mfma_f32_32x32x16_bf16 v[66:81], v[22:25], v[2:5], 0
	v_cmp_lt_i32_e32 vcc, 23, v51
	s_and_b64 s[24:25], vcc, s[16:17]
	v_cmp_lt_i32_e32 vcc, 24, v51
	s_and_b64 s[18:19], vcc, s[16:17]
	v_cmp_lt_i32_e32 vcc, 25, v51
	s_and_b64 s[20:21], vcc, s[16:17]
	v_cmp_lt_i32_e32 vcc, 26, v51
	s_and_b64 vcc, vcc, s[16:17]
	v_cmp_ne_u32_e64 s[16:17], 1, v50
	s_waitcnt vmcnt(2)
	v_mfma_f32_32x32x16_bf16 v[82:97], v[10:13], v[132:135], v[82:97]
	s_mov_b32 s1, 0xf149f2ca
	v_mfma_f32_32x32x16_bf16 v[66:81], v[26:29], v[132:135], v[66:81]
	v_mfma_f32_32x32x16_bf16 v[50:65], v[38:41], v[2:5], 0
	s_waitcnt vmcnt(1)
	v_mfma_f32_32x32x16_bf16 v[82:97], v[14:17], v[136:139], v[82:97]
	v_mfma_f32_32x32x16_bf16 v[66:81], v[30:33], v[136:139], v[66:81]
	v_mfma_f32_32x32x16_bf16 v[50:65], v[42:45], v[132:135], v[50:65]
	s_waitcnt vmcnt(0)
	v_mfma_f32_32x32x16_bf16 v[82:97], v[18:21], v[140:143], v[82:97]
	v_mfma_f32_32x32x16_bf16 v[66:81], v[34:37], v[140:143], v[66:81]
	s_waitcnt lgkmcnt(13)
	v_mfma_f32_32x32x16_bf16 v[50:65], v[46:49], v[136:139], v[50:65]
	s_waitcnt lgkmcnt(11)
	v_mfma_f32_32x32x16_bf16 v[34:49], v[148:151], v[2:5], 0
	s_waitcnt lgkmcnt(7)
	v_mfma_f32_32x32x16_bf16 v[18:33], v[180:183], v[2:5], 0
	s_waitcnt lgkmcnt(3)
	v_mfma_f32_32x32x16_bf16 v[2:17], v[164:167], v[2:5], 0
	s_waitcnt lgkmcnt(2)
	v_mfma_f32_32x32x16_bf16 v[2:17], v[168:171], v[132:135], v[2:17]
	v_mfma_f32_32x32x16_bf16 v[34:49], v[152:155], v[132:135], v[34:49]
	v_mfma_f32_32x32x16_bf16 v[18:33], v[184:187], v[132:135], v[18:33]
	s_waitcnt lgkmcnt(1)
	v_mfma_f32_32x32x16_bf16 v[2:17], v[172:175], v[136:139], v[2:17]
	v_mfma_f32_32x32x16_bf16 v[34:49], v[156:159], v[136:139], v[34:49]
	v_mfma_f32_32x32x16_bf16 v[18:33], v[188:191], v[136:139], v[18:33]
	s_waitcnt lgkmcnt(0)
	v_mfma_f32_32x32x16_bf16 v[2:17], v[176:179], v[140:143], v[2:17]
	v_mfma_f32_32x32x16_bf16 v[50:65], v[144:147], v[140:143], v[50:65]
	s_nop 10
	v_mul_f32_e32 v12, 0x3fb8aa3b, v83
	v_cndmask_b32_e64 v144, v226, v12, s[82:83]
	v_mul_f32_e32 v12, 0x3fb8aa3b, v84
	v_mul_f32_e32 v10, 0x3fb8aa3b, v82
	v_cndmask_b32_e64 v10, v226, v10, s[86:87]
	v_max_f32_e32 v11, v201, v201
	v_max_f32_e32 v11, v11, v10
	v_mfma_f32_32x32x16_bf16 v[34:49], v[160:163], v[140:143], v[34:49]
	v_mfma_f32_32x32x16_bf16 v[18:33], v[192:195], v[140:143], v[18:33]
	v_cndmask_b32_e64 v142, v226, v12, s[84:85]
	v_mul_f32_e32 v12, 0x3fb8aa3b, v85
	v_cndmask_b32_e64 v143, v226, v12, s[78:79]
	v_mul_f32_e32 v12, 0x3fb8aa3b, v86
	v_cndmask_b32_e64 v140, v226, v12, s[80:81]
	v_mul_f32_e32 v12, 0x3fb8aa3b, v87
	v_cndmask_b32_e64 v141, v226, v12, s[74:75]
	v_mul_f32_e32 v12, 0x3fb8aa3b, v88
	v_cndmask_b32_e64 v138, v226, v12, s[76:77]
	v_mul_f32_e32 v12, 0x3fb8aa3b, v89
	v_cndmask_b32_e64 v139, v226, v12, s[70:71]
	v_mul_f32_e32 v12, 0x3fb8aa3b, v90
	v_cndmask_b32_e64 v136, v226, v12, s[72:73]
	v_mul_f32_e32 v12, 0x3fb8aa3b, v91
	v_max3_f32 v11, v11, v144, v142
	v_cndmask_b32_e64 v137, v226, v12, s[66:67]
	v_mul_f32_e32 v12, 0x3fb8aa3b, v92
	v_max3_f32 v11, v11, v143, v140
	v_cndmask_b32_e64 v134, v226, v12, s[68:69]
	v_mul_f32_e32 v12, 0x3fb8aa3b, v93
	v_max3_f32 v11, v11, v141, v138
	v_cndmask_b32_e64 v135, v226, v12, s[62:63]
	v_mul_f32_e32 v12, 0x3fb8aa3b, v94
	v_max3_f32 v11, v11, v139, v136
	v_cndmask_b32_e64 v132, v226, v12, s[64:65]
	v_mul_f32_e32 v12, 0x3fb8aa3b, v95
	v_max3_f32 v11, v11, v137, v134
	v_cndmask_b32_e64 v133, v226, v12, s[58:59]
	v_mul_f32_e32 v12, 0x3fb8aa3b, v96
	v_max3_f32 v11, v11, v135, v132
	v_cndmask_b32_e64 v95, v226, v12, s[60:61]
	v_max3_f32 v145, v11, v133, v95
	v_mul_f32_e32 v11, 0x3fb8aa3b, v97
	v_cndmask_b32_e64 v96, v226, v11, s[56:57]
	v_mul_f32_e32 v11, 0x3fb8aa3b, v66
	v_cndmask_b32_e64 v94, v226, v11, s[54:55]
	v_mul_f32_e32 v11, 0x3fb8aa3b, v67
	v_cndmask_b32_e64 v93, v226, v11, s[54:55]
	v_mul_f32_e32 v11, 0x3fb8aa3b, v68
	v_cndmask_b32_e64 v92, v226, v11, s[54:55]
	v_mul_f32_e32 v11, 0x3fb8aa3b, v69
	v_cndmask_b32_e64 v91, v226, v11, s[54:55]
	v_mul_f32_e32 v11, 0x3fb8aa3b, v70
	v_cndmask_b32_e64 v90, v226, v11, s[54:55]
	v_mul_f32_e32 v11, 0x3fb8aa3b, v71
	v_cndmask_b32_e64 v89, v226, v11, s[54:55]
	v_mul_f32_e32 v11, 0x3fb8aa3b, v72
	v_cndmask_b32_e64 v88, v226, v11, s[54:55]
	v_mul_f32_e32 v11, 0x3fb8aa3b, v73
	v_cndmask_b32_e64 v87, v226, v11, s[54:55]
	v_mul_f32_e32 v11, 0x3fb8aa3b, v74
	v_cndmask_b32_e64 v86, v226, v11, s[54:55]
	v_mul_f32_e32 v11, 0x3fb8aa3b, v75
	v_cndmask_b32_e64 v85, v226, v11, s[54:55]
	v_mul_f32_e32 v11, 0x3fb8aa3b, v76
	v_cndmask_b32_e64 v84, v226, v11, s[54:55]
	v_mul_f32_e32 v11, 0x3fb8aa3b, v77
	v_cndmask_b32_e64 v83, v226, v11, s[54:55]
	v_mul_f32_e32 v11, 0x3fb8aa3b, v78
	v_cndmask_b32_e64 v82, v226, v11, s[54:55]
	v_mul_f32_e32 v11, 0x3fb8aa3b, v79
	v_cndmask_b32_e64 v78, v226, v11, s[54:55]
	v_mul_f32_e32 v11, 0x3fb8aa3b, v80
	v_cndmask_b32_e64 v77, v226, v11, s[54:55]
	v_mul_f32_e32 v11, 0x3fb8aa3b, v81
	v_cndmask_b32_e64 v76, v226, v11, s[54:55]
	v_mul_f32_e32 v11, 0x3fb8aa3b, v50
	v_cndmask_b32_e64 v75, v226, v11, s[52:53]
	v_mul_f32_e32 v11, 0x3fb8aa3b, v51
	v_cndmask_b32_e64 v74, v226, v11, s[52:53]
	v_mul_f32_e32 v11, 0x3fb8aa3b, v52
	v_cndmask_b32_e64 v73, v226, v11, s[52:53]
	v_mul_f32_e32 v11, 0x3fb8aa3b, v53
	v_cndmask_b32_e64 v72, v226, v11, s[52:53]
	v_mul_f32_e32 v11, 0x3fb8aa3b, v54
	v_cndmask_b32_e64 v71, v226, v11, s[52:53]
	v_mul_f32_e32 v11, 0x3fb8aa3b, v55
	v_cndmask_b32_e64 v70, v226, v11, s[52:53]
	v_mul_f32_e32 v11, 0x3fb8aa3b, v56
	v_cndmask_b32_e64 v69, v226, v11, s[52:53]
	v_mul_f32_e32 v11, 0x3fb8aa3b, v57
	v_cndmask_b32_e64 v68, v226, v11, s[52:53]
	v_mul_f32_e32 v11, 0x3fb8aa3b, v58
	v_cndmask_b32_e64 v67, v226, v11, s[52:53]
	v_mul_f32_e32 v11, 0x3fb8aa3b, v59
	v_cndmask_b32_e64 v66, v226, v11, s[52:53]
	v_mul_f32_e32 v11, 0x3fb8aa3b, v60
	v_cndmask_b32_e64 v59, v226, v11, s[52:53]
	v_mul_f32_e32 v11, 0x3fb8aa3b, v61
	v_cndmask_b32_e64 v58, v226, v11, s[52:53]
	v_mul_f32_e32 v11, 0x3fb8aa3b, v62
	v_cndmask_b32_e64 v57, v226, v11, s[52:53]
	v_mul_f32_e32 v11, 0x3fb8aa3b, v63
	v_cndmask_b32_e64 v56, v226, v11, s[52:53]
	v_mul_f32_e32 v11, 0x3fb8aa3b, v64
	v_cndmask_b32_e64 v55, v226, v11, s[52:53]
	v_mul_f32_e32 v11, 0x3fb8aa3b, v65
	v_cndmask_b32_e64 v54, v226, v11, s[52:53]
	v_mul_f32_e32 v11, 0x3fb8aa3b, v34
	v_cndmask_b32_e64 v53, v226, v11, s[36:37]
	v_mul_f32_e32 v11, 0x3fb8aa3b, v35
	v_cndmask_b32_e64 v52, v226, v11, s[36:37]
	v_mul_f32_e32 v11, 0x3fb8aa3b, v36
	v_cndmask_b32_e64 v51, v226, v11, s[36:37]
	v_mul_f32_e32 v11, 0x3fb8aa3b, v37
	v_cndmask_b32_e64 v50, v226, v11, s[36:37]
	v_mul_f32_e32 v11, 0x3fb8aa3b, v38
	v_max3_f32 v38, v145, v96, v94
	v_max3_f32 v38, v38, v93, v92
	v_max3_f32 v38, v38, v91, v90
	v_max3_f32 v38, v38, v89, v88
	v_max3_f32 v38, v38, v87, v86
	v_max3_f32 v38, v38, v85, v84
	v_max3_f32 v38, v38, v83, v82
	v_max3_f32 v38, v38, v78, v77
	v_max3_f32 v38, v38, v76, v75
	v_max3_f32 v38, v38, v74, v73
	v_max3_f32 v38, v38, v72, v71
	v_max3_f32 v38, v38, v70, v69
	v_cndmask_b32_e64 v37, v226, v11, s[36:37]
	v_mul_f32_e32 v11, 0x3fb8aa3b, v39
	v_max3_f32 v38, v38, v68, v67
	v_cndmask_b32_e64 v36, v226, v11, s[36:37]
	v_mul_f32_e32 v11, 0x3fb8aa3b, v40
	v_max3_f32 v38, v38, v66, v59
	v_cndmask_b32_e64 v35, v226, v11, s[36:37]
	v_mul_f32_e32 v11, 0x3fb8aa3b, v41
	v_max3_f32 v38, v38, v58, v57
	v_cndmask_b32_e64 v34, v226, v11, s[36:37]
	v_mul_f32_e32 v11, 0x3fb8aa3b, v42
	v_max3_f32 v38, v38, v56, v55
	v_cndmask_b32_e64 v17, v226, v11, s[36:37]
	v_mul_f32_e32 v11, 0x3fb8aa3b, v43
	v_max3_f32 v38, v38, v54, v53
	v_cndmask_b32_e64 v16, v226, v11, s[36:37]
	v_mul_f32_e32 v11, 0x3fb8aa3b, v44
	v_max3_f32 v38, v38, v52, v51
	v_cndmask_b32_e64 v15, v226, v11, s[36:37]
	v_mul_f32_e32 v11, 0x3fb8aa3b, v45
	v_max3_f32 v38, v38, v50, v37
	v_mul_f32_e32 v19, 0x3fb8aa3b, v19
	v_cndmask_b32_e64 v14, v226, v11, s[36:37]
	v_mul_f32_e32 v11, 0x3fb8aa3b, v46
	v_max3_f32 v38, v38, v36, v35
	v_cndmask_b32_e64 v45, v226, v19, s[46:47]
	v_mul_f32_e32 v19, 0x3fb8aa3b, v20
	v_cndmask_b32_e64 v13, v226, v11, s[36:37]
	v_mul_f32_e32 v11, 0x3fb8aa3b, v47
	v_max3_f32 v38, v38, v34, v17
	v_cndmask_b32_e64 v42, v226, v19, s[48:49]
	v_mul_f32_e32 v19, 0x3fb8aa3b, v21
	v_cndmask_b32_e64 v12, v226, v11, s[36:37]
	v_mul_f32_e32 v11, 0x3fb8aa3b, v48
	v_max3_f32 v38, v38, v16, v15
	v_cndmask_b32_e64 v43, v226, v19, s[42:43]
	v_mul_f32_e32 v19, 0x3fb8aa3b, v22
	v_cndmask_b32_e64 v11, v226, v11, s[36:37]
	v_max3_f32 v38, v38, v14, v13
	v_mul_f32_e32 v39, 0x3fb8aa3b, v49
	v_mul_f32_e32 v18, 0x3fb8aa3b, v18
	v_cndmask_b32_e64 v40, v226, v19, s[44:45]
	v_mul_f32_e32 v19, 0x3fb8aa3b, v23
	v_max3_f32 v38, v38, v12, v11
	v_cndmask_b32_e64 v46, v226, v39, s[36:37]
	v_cndmask_b32_e64 v44, v226, v18, s[50:51]
	v_cndmask_b32_e64 v41, v226, v19, s[38:39]
	v_mul_f32_e32 v19, 0x3fb8aa3b, v24
	v_max3_f32 v18, v38, v46, v44
	v_cndmask_b32_e64 v38, v226, v19, s[40:41]
	v_mul_f32_e32 v19, 0x3fb8aa3b, v25
	v_cndmask_b32_e64 v39, v226, v19, s[30:31]
	v_mul_f32_e32 v19, 0x3fb8aa3b, v26
	v_max3_f32 v18, v18, v45, v42
	v_cndmask_b32_e64 v24, v226, v19, s[34:35]
	v_mul_f32_e32 v19, 0x3fb8aa3b, v27
	v_max3_f32 v18, v18, v43, v40
	v_cndmask_b32_e64 v25, v226, v19, s[26:27]
	v_mul_f32_e32 v19, 0x3fb8aa3b, v28
	v_max3_f32 v18, v18, v41, v38
	v_cndmask_b32_e64 v22, v226, v19, s[28:29]
	v_mul_f32_e32 v19, 0x3fb8aa3b, v29
	v_max3_f32 v18, v18, v39, v24
	v_cndmask_b32_e64 v23, v226, v19, s[22:23]
	v_mul_f32_e32 v19, 0x3fb8aa3b, v30
	v_max3_f32 v18, v18, v25, v22
	v_cndmask_b32_e64 v20, v226, v19, s[24:25]
	v_max3_f32 v19, v18, v23, v20
	v_mul_f32_e32 v18, 0x3fb8aa3b, v31
	v_cndmask_b32_e64 v21, v226, v18, s[18:19]
	v_mul_f32_e32 v18, 0x3fb8aa3b, v32
	v_cndmask_b32_e64 v18, v226, v18, s[20:21]
	v_max3_f32 v26, v19, v21, v18
	v_mul_f32_e32 v19, 0x3fb8aa3b, v33
	v_cndmask_b32_e32 v19, v226, v19, vcc
	v_mul_f32_e32 v27, 0x3fb8aa3b, v2
	v_max3_f32 v26, v26, v19, v27
	v_mul_f32_e32 v27, 0x3fb8aa3b, v3
	v_mul_f32_e32 v28, 0x3fb8aa3b, v4
	v_max3_f32 v26, v26, v27, v28
	v_mul_f32_e32 v27, 0x3fb8aa3b, v5
	v_mul_f32_e32 v28, 0x3fb8aa3b, v6
	v_max3_f32 v26, v26, v27, v28
	v_mul_f32_e32 v27, 0x3fb8aa3b, v7
	v_mul_f32_e32 v28, 0x3fb8aa3b, v8
	v_max3_f32 v26, v26, v27, v28
	v_mul_f32_e32 v27, 0x3fb8aa3b, v9
	v_and_b32_e32 v28, 64, v232
	v_max3_f32 v26, v26, v27, s1
	v_xor_b32_e32 v27, 32, v232
	v_add_u32_e32 v28, 64, v28
	v_cmp_lt_i32_e32 vcc, v27, v28
	s_mov_b64 s[18:19], 0
	s_nop 0
	v_cndmask_b32_e32 v27, v232, v27, vcc
	v_lshlrev_b32_e32 v27, 2, v27
	ds_bpermute_b32 v28, v27, v26
	s_waitcnt lgkmcnt(0)
	v_max_f32_e32 v28, v28, v28
	v_max_f32_e32 v26, v26, v28
	v_sub_f32_e32 v10, v10, v26
	v_exp_f32_e32 v10, v10
	v_sub_f32_e32 v29, v144, v26
	v_exp_f32_e32 v29, v29
	v_sub_f32_e32 v30, v142, v26
	v_exp_f32_e32 v30, v30
	v_sub_f32_e32 v31, v143, v26
	v_exp_f32_e32 v31, v31
	v_sub_f32_e32 v32, v140, v26
	v_add_f32_e32 v28, 0, v10
	v_exp_f32_e32 v32, v32
	v_sub_f32_e32 v33, v141, v26
	v_add_f32_e32 v28, v28, v29
	v_exp_f32_e32 v33, v33
	v_sub_f32_e32 v47, v138, v26
	v_add_f32_e32 v28, v28, v30
	v_exp_f32_e32 v47, v47
	v_sub_f32_e32 v48, v139, v26
	v_add_f32_e32 v28, v28, v31
	v_exp_f32_e32 v48, v48
	v_sub_f32_e32 v49, v136, v26
	v_add_f32_e32 v28, v28, v32
	v_exp_f32_e32 v49, v49
	v_sub_f32_e32 v60, v137, v26
	v_add_f32_e32 v28, v28, v33
	v_exp_f32_e32 v60, v60
	v_sub_f32_e32 v61, v134, v26
	v_add_f32_e32 v28, v28, v47
	v_exp_f32_e32 v61, v61
	v_sub_f32_e32 v62, v135, v26
	v_add_f32_e32 v28, v28, v48
	v_exp_f32_e32 v62, v62
	v_sub_f32_e32 v63, v132, v26
	v_add_f32_e32 v28, v28, v49
	v_exp_f32_e32 v63, v63
	v_sub_f32_e32 v64, v133, v26
	v_add_f32_e32 v28, v28, v60
	v_exp_f32_e32 v64, v64
	v_sub_f32_e32 v65, v95, v26
	v_add_f32_e32 v28, v28, v61
	v_exp_f32_e32 v65, v65
	v_sub_f32_e32 v79, v96, v26
	v_add_f32_e32 v28, v28, v62
	v_exp_f32_e32 v79, v79
	v_sub_f32_e32 v80, v94, v26
	v_add_f32_e32 v28, v28, v63
	v_exp_f32_e32 v80, v80
	v_sub_f32_e32 v81, v93, v26
	v_add_f32_e32 v28, v28, v64
	v_exp_f32_e32 v81, v81
	v_sub_f32_e32 v92, v92, v26
	v_add_f32_e32 v28, v28, v65
	v_exp_f32_e32 v92, v92
	v_sub_f32_e32 v91, v91, v26
	v_add_f32_e32 v28, v28, v79
	v_exp_f32_e32 v91, v91
	v_sub_f32_e32 v90, v90, v26
	v_add_f32_e32 v28, v28, v80
	v_exp_f32_e32 v90, v90
	v_sub_f32_e32 v89, v89, v26
	v_add_f32_e32 v28, v28, v81
	v_exp_f32_e32 v89, v89
	v_sub_f32_e32 v88, v88, v26
	v_add_f32_e32 v28, v28, v92
	v_exp_f32_e32 v88, v88
	v_sub_f32_e32 v87, v87, v26
	v_add_f32_e32 v28, v28, v91
	v_exp_f32_e32 v87, v87
	v_sub_f32_e32 v86, v86, v26
	v_add_f32_e32 v28, v28, v90
	v_exp_f32_e32 v86, v86
	v_sub_f32_e32 v85, v85, v26
	v_add_f32_e32 v28, v28, v89
	v_exp_f32_e32 v85, v85
	v_sub_f32_e32 v84, v84, v26
	v_add_f32_e32 v28, v28, v88
	v_exp_f32_e32 v84, v84
	v_sub_f32_e32 v83, v83, v26
	v_add_f32_e32 v28, v28, v87
	v_exp_f32_e32 v83, v83
	v_sub_f32_e32 v82, v82, v26
	v_add_f32_e32 v28, v28, v86
	v_exp_f32_e32 v82, v82
	v_sub_f32_e32 v78, v78, v26
	v_add_f32_e32 v28, v28, v85
	v_exp_f32_e32 v78, v78
	v_sub_f32_e32 v77, v77, v26
	v_add_f32_e32 v28, v28, v84
	v_exp_f32_e32 v77, v77
	v_sub_f32_e32 v76, v76, v26
	v_add_f32_e32 v28, v28, v83
	v_exp_f32_e32 v76, v76
	v_sub_f32_e32 v75, v75, v26
	v_add_f32_e32 v28, v28, v82
	v_exp_f32_e32 v75, v75
	v_sub_f32_e32 v74, v74, v26
	v_add_f32_e32 v28, v28, v78
	v_exp_f32_e32 v74, v74
	v_sub_f32_e32 v73, v73, v26
	v_add_f32_e32 v28, v28, v77
	v_exp_f32_e32 v73, v73
	v_sub_f32_e32 v72, v72, v26
	v_add_f32_e32 v28, v28, v76
	v_exp_f32_e32 v72, v72
	v_sub_f32_e32 v71, v71, v26
	v_add_f32_e32 v28, v28, v75
	v_exp_f32_e32 v71, v71
	v_sub_f32_e32 v70, v70, v26
	v_add_f32_e32 v28, v28, v74
	v_exp_f32_e32 v70, v70
	v_sub_f32_e32 v69, v69, v26
	v_add_f32_e32 v28, v28, v73
	v_exp_f32_e32 v69, v69
	v_sub_f32_e32 v68, v68, v26
	v_add_f32_e32 v28, v28, v72
	v_exp_f32_e32 v68, v68
	v_sub_f32_e32 v67, v67, v26
	v_add_f32_e32 v28, v28, v71
	v_exp_f32_e32 v67, v67
	v_sub_f32_e32 v66, v66, v26
	v_add_f32_e32 v28, v28, v70
	v_exp_f32_e32 v66, v66
	v_sub_f32_e32 v59, v59, v26
	v_add_f32_e32 v28, v28, v69
	v_exp_f32_e32 v59, v59
	v_sub_f32_e32 v58, v58, v26
	v_add_f32_e32 v28, v28, v68
	v_exp_f32_e32 v58, v58
	v_sub_f32_e32 v57, v57, v26
	v_add_f32_e32 v28, v28, v67
	v_exp_f32_e32 v57, v57
	v_sub_f32_e32 v56, v56, v26
	v_add_f32_e32 v28, v28, v66
	v_exp_f32_e32 v56, v56
	v_sub_f32_e32 v55, v55, v26
	v_add_f32_e32 v28, v28, v59
	v_exp_f32_e32 v55, v55
	v_sub_f32_e32 v54, v54, v26
	v_add_f32_e32 v28, v28, v58
	v_exp_f32_e32 v54, v54
	v_sub_f32_e32 v53, v53, v26
	v_add_f32_e32 v28, v28, v57
	v_exp_f32_e32 v53, v53
	v_sub_f32_e32 v52, v52, v26
	v_add_f32_e32 v28, v28, v56
	v_exp_f32_e32 v52, v52
	v_sub_f32_e32 v51, v51, v26
	v_add_f32_e32 v28, v28, v55
	v_exp_f32_e32 v51, v51
	v_sub_f32_e32 v50, v50, v26
	v_add_f32_e32 v28, v28, v54
	v_exp_f32_e32 v50, v50
	v_sub_f32_e32 v37, v37, v26
	v_add_f32_e32 v28, v28, v53
	v_exp_f32_e32 v93, v37
	v_sub_f32_e32 v36, v36, v26
	v_add_f32_e32 v28, v28, v52
	v_exp_f32_e32 v94, v36
	v_sub_f32_e32 v35, v35, v26
	v_add_f32_e32 v28, v28, v51
	v_exp_f32_e32 v95, v35
	v_sub_f32_e32 v34, v34, v26
	v_add_f32_e32 v28, v28, v50
	v_exp_f32_e32 v96, v34
	v_sub_f32_e32 v17, v17, v26
	v_add_f32_e32 v28, v28, v93
	v_exp_f32_e32 v97, v17
	v_sub_f32_e32 v16, v16, v26
	v_add_f32_e32 v28, v28, v94
	v_exp_f32_e32 v132, v16
	v_sub_f32_e32 v15, v15, v26
	v_add_f32_e32 v28, v28, v95
	v_exp_f32_e32 v133, v15
	v_sub_f32_e32 v14, v14, v26
	v_add_f32_e32 v28, v28, v96
	v_exp_f32_e32 v134, v14
	v_sub_f32_e32 v13, v13, v26
	v_add_f32_e32 v17, v28, v97
	v_exp_f32_e32 v135, v13
	v_sub_f32_e32 v12, v12, v26
	v_add_f32_e32 v16, v17, v132
	v_exp_f32_e32 v136, v12
	v_sub_f32_e32 v11, v11, v26
	v_add_f32_e32 v15, v16, v133
	v_exp_f32_e32 v137, v11
	v_add_f32_e32 v14, v15, v134
	v_add_f32_e32 v13, v14, v135
	v_add_f32_e32 v12, v13, v136
	v_add_f32_e32 v11, v12, v137
	v_sub_f32_e32 v12, v46, v26
	v_exp_f32_e32 v46, v12
	v_sub_f32_e32 v12, v44, v26
	v_exp_f32_e32 v138, v12
	v_sub_f32_e32 v12, v45, v26
	v_exp_f32_e32 v139, v12
	v_sub_f32_e32 v12, v42, v26
	v_exp_f32_e32 v140, v12
	v_sub_f32_e32 v12, v43, v26
	v_add_f32_e32 v11, v11, v46
	v_exp_f32_e32 v141, v12
	v_sub_f32_e32 v12, v40, v26
	v_add_f32_e32 v11, v11, v138
	v_exp_f32_e32 v142, v12
	v_sub_f32_e32 v12, v41, v26
	v_add_f32_e32 v11, v11, v139
	v_exp_f32_e32 v143, v12
	v_sub_f32_e32 v12, v38, v26
	v_add_f32_e32 v11, v11, v140
	v_exp_f32_e32 v144, v12
	v_sub_f32_e32 v12, v39, v26
	v_add_f32_e32 v11, v11, v141
	v_exp_f32_e32 v145, v12
	v_sub_f32_e32 v12, v24, v26
	v_add_f32_e32 v11, v11, v142
	v_exp_f32_e32 v146, v12
	v_sub_f32_e32 v12, v25, v26
	v_add_f32_e32 v11, v11, v143
	v_exp_f32_e32 v147, v12
	v_sub_f32_e32 v12, v22, v26
	v_add_f32_e32 v11, v11, v144
	v_exp_f32_e32 v148, v12
	v_sub_f32_e32 v12, v23, v26
	v_add_f32_e32 v11, v11, v145
	v_exp_f32_e32 v149, v12
	v_sub_f32_e32 v12, v20, v26
	v_add_f32_e32 v11, v11, v146
	v_exp_f32_e32 v150, v12
	v_sub_f32_e32 v12, v21, v26
	v_add_f32_e32 v11, v11, v147
	v_exp_f32_e32 v151, v12
	v_sub_f32_e32 v12, v18, v26
	v_add_f32_e32 v11, v11, v148
	v_exp_f32_e32 v152, v12
	v_sub_f32_e32 v12, v19, v26
	v_add_f32_e32 v11, v11, v149
	v_exp_f32_e32 v153, v12
	v_fma_f32 v2, v2, s9, -v26
	v_add_f32_e32 v11, v11, v150
	v_exp_f32_e32 v154, v2
	v_fma_f32 v3, v3, s9, -v26
	v_add_f32_e32 v11, v11, v151
	v_exp_f32_e32 v155, v3
	v_fma_f32 v3, v4, s9, -v26
	v_add_f32_e32 v11, v11, v152
	v_exp_f32_e32 v156, v3
	v_fma_f32 v3, v5, s9, -v26
	v_add_f32_e32 v11, v11, v153
	v_exp_f32_e32 v157, v3
	v_fma_f32 v3, v6, s9, -v26
	v_add_f32_e32 v2, v11, v154
	v_exp_f32_e32 v158, v3
	v_fma_f32 v3, v7, s9, -v26
	v_add_f32_e32 v2, v2, v155
	v_exp_f32_e32 v159, v3
	v_fma_f32 v3, v8, s9, -v26
	v_add_f32_e32 v2, v2, v156
	v_exp_f32_e32 v160, v3
	v_fma_f32 v3, v9, s9, -v26
	v_add_f32_e32 v2, v2, v157
	v_exp_f32_e32 v161, v3
	v_sub_f32_e32 v3, 0xf149f2ca, v26
	v_add_f32_e32 v2, v2, v158
	v_exp_f32_e32 v162, v3
	v_add_f32_e32 v2, v2, v159
	v_add_f32_e32 v2, v2, v160
	v_add_f32_e32 v2, v2, v161
	v_add_f32_e32 v2, v2, v162
	v_add_f32_e32 v2, v2, v162
	v_add_f32_e32 v2, v2, v162
	v_add_f32_e32 v2, v2, v162
	v_add_f32_e32 v2, v2, v162
	v_add_f32_e32 v2, v2, v162
	v_add_f32_e32 v2, v2, v162
	v_add_f32_e32 v163, v2, v162
	v_sub_f32_e32 v2, v201, v26
	v_add_u32_e32 v44, s7, v223
	v_exp_f32_e32 v165, v2
	s_nop 0
	v_cvt_pk_bf16_f32 v2, v10, v29
	s_nop 0
	v_cvt_pk_bf16_f32 v3, v30, v31
	s_nop 0
	v_cvt_pk_bf16_f32 v4, v32, v33
	s_nop 0
	v_cvt_pk_bf16_f32 v5, v47, v48
	ds_read_b64_tr_b16 v[6:7], v44 offset:32256
	ds_read_b64_tr_b16 v[8:9], v44 offset:33408
	ds_read_b64_tr_b16 v[10:11], v44 offset:32320
	ds_read_b64_tr_b16 v[12:13], v44 offset:33472
	ds_bpermute_b32 v164, v27, v163
	s_waitcnt lgkmcnt(3)
	v_mfma_f32_32x32x16_bf16 v[18:33], v[6:9], v[2:5], 0
	s_nop 0
	v_cvt_pk_bf16_f32 v34, v49, v60
	s_nop 0
	v_cvt_pk_bf16_f32 v35, v61, v62
	s_nop 0
	v_cvt_pk_bf16_f32 v36, v63, v64
	s_nop 0
	v_cvt_pk_bf16_f32 v37, v65, v79
	ds_read_b64_tr_b16 v[38:39], v44 offset:34560
	ds_read_b64_tr_b16 v[40:41], v44 offset:35712
	ds_read_b64_tr_b16 v[42:43], v44 offset:34624
	ds_read_b64_tr_b16 v[44:45], v44 offset:35776
	v_add_u32_e32 v47, s6, v223
	s_waitcnt lgkmcnt(5)
	v_mfma_f32_32x32x16_bf16 v[2:17], v[10:13], v[2:5], 0
	s_waitcnt lgkmcnt(2)
	v_mfma_f32_32x32x16_bf16 v[18:33], v[38:41], v[34:37], v[18:33]
	s_waitcnt lgkmcnt(0)
	v_mfma_f32_32x32x16_bf16 v[2:17], v[42:45], v[34:37], v[2:17]
	s_nop 0
	v_cvt_pk_bf16_f32 v34, v80, v81
	s_nop 0
	v_cvt_pk_bf16_f32 v35, v92, v91
	s_nop 0
	v_cvt_pk_bf16_f32 v36, v90, v89
	s_nop 0
	v_cvt_pk_bf16_f32 v37, v88, v87
	ds_read_b64_tr_b16 v[38:39], v47 offset:32256
	ds_read_b64_tr_b16 v[40:41], v47 offset:33408
	ds_read_b64_tr_b16 v[42:43], v47 offset:32320
	ds_read_b64_tr_b16 v[44:45], v47 offset:33472
	s_waitcnt lgkmcnt(2)
	v_mfma_f32_32x32x16_bf16 v[18:33], v[38:41], v[34:37], v[18:33]
	s_waitcnt lgkmcnt(0)
	v_mfma_f32_32x32x16_bf16 v[2:17], v[42:45], v[34:37], v[2:17]
	s_nop 0
	v_cvt_pk_bf16_f32 v34, v86, v85
	s_nop 0
	v_cvt_pk_bf16_f32 v35, v84, v83
	s_nop 0
	v_cvt_pk_bf16_f32 v36, v82, v78
	s_nop 0
	v_cvt_pk_bf16_f32 v37, v77, v76
	ds_read_b64_tr_b16 v[38:39], v47 offset:34560
	ds_read_b64_tr_b16 v[40:41], v47 offset:35712
	ds_read_b64_tr_b16 v[42:43], v47 offset:34624
	ds_read_b64_tr_b16 v[44:45], v47 offset:35776
	v_add_u32_e32 v47, s15, v223
	s_waitcnt lgkmcnt(2)
	v_mfma_f32_32x32x16_bf16 v[18:33], v[38:41], v[34:37], v[18:33]
	s_waitcnt lgkmcnt(0)
	v_mfma_f32_32x32x16_bf16 v[2:17], v[42:45], v[34:37], v[2:17]
	s_nop 0
	v_cvt_pk_bf16_f32 v34, v75, v74
	s_nop 0
	v_cvt_pk_bf16_f32 v35, v73, v72
	s_nop 0
	v_cvt_pk_bf16_f32 v36, v71, v70
	s_nop 0
	v_cvt_pk_bf16_f32 v37, v69, v68
	ds_read_b64_tr_b16 v[38:39], v47 offset:32256
	ds_read_b64_tr_b16 v[40:41], v47 offset:33408
	ds_read_b64_tr_b16 v[42:43], v47 offset:32320
	ds_read_b64_tr_b16 v[44:45], v47 offset:33472
	s_waitcnt lgkmcnt(2)
	v_mfma_f32_32x32x16_bf16 v[18:33], v[38:41], v[34:37], v[18:33]
	s_waitcnt lgkmcnt(0)
	v_mfma_f32_32x32x16_bf16 v[2:17], v[42:45], v[34:37], v[2:17]
	s_nop 0
	v_cvt_pk_bf16_f32 v34, v67, v66
	s_nop 0
	v_cvt_pk_bf16_f32 v35, v59, v58
	s_nop 0
	v_cvt_pk_bf16_f32 v36, v57, v56
	s_nop 0
	v_cvt_pk_bf16_f32 v37, v55, v54
	ds_read_b64_tr_b16 v[38:39], v47 offset:34560
	ds_read_b64_tr_b16 v[40:41], v47 offset:35712
	ds_read_b64_tr_b16 v[42:43], v47 offset:34624
	ds_read_b64_tr_b16 v[44:45], v47 offset:35776
	v_add_u32_e32 v47, s14, v223
	s_waitcnt lgkmcnt(2)
	v_mfma_f32_32x32x16_bf16 v[18:33], v[38:41], v[34:37], v[18:33]
	s_waitcnt lgkmcnt(0)
	v_mfma_f32_32x32x16_bf16 v[2:17], v[42:45], v[34:37], v[2:17]
	s_nop 0
	v_cvt_pk_bf16_f32 v34, v53, v52
	s_nop 0
	v_cvt_pk_bf16_f32 v35, v51, v50
	s_nop 0
	v_cvt_pk_bf16_f32 v36, v93, v94
	s_nop 0
	v_cvt_pk_bf16_f32 v37, v95, v96
	ds_read_b64_tr_b16 v[38:39], v47 offset:32256
	ds_read_b64_tr_b16 v[40:41], v47 offset:33408
	ds_read_b64_tr_b16 v[42:43], v47 offset:32320
	ds_read_b64_tr_b16 v[44:45], v47 offset:33472
	s_waitcnt lgkmcnt(2)
	v_mfma_f32_32x32x16_bf16 v[18:33], v[38:41], v[34:37], v[18:33]
	s_waitcnt lgkmcnt(0)
	v_mfma_f32_32x32x16_bf16 v[2:17], v[42:45], v[34:37], v[2:17]
	s_nop 0
	v_cvt_pk_bf16_f32 v34, v97, v132
	s_nop 0
	v_cvt_pk_bf16_f32 v35, v133, v134
	s_nop 0
	v_cvt_pk_bf16_f32 v36, v135, v136
	s_nop 0
	v_cvt_pk_bf16_f32 v37, v137, v46
	ds_read_b64_tr_b16 v[38:39], v47 offset:34560
	ds_read_b64_tr_b16 v[40:41], v47 offset:35712
	ds_read_b64_tr_b16 v[42:43], v47 offset:34624
	ds_read_b64_tr_b16 v[44:45], v47 offset:35776
	v_add_u32_e32 v46, s0, v223
	s_waitcnt lgkmcnt(2)
	v_mfma_f32_32x32x16_bf16 v[18:33], v[38:41], v[34:37], v[18:33]
	s_waitcnt lgkmcnt(0)
	v_mfma_f32_32x32x16_bf16 v[2:17], v[42:45], v[34:37], v[2:17]
	s_nop 0
	v_cvt_pk_bf16_f32 v34, v138, v139
	s_nop 0
	v_cvt_pk_bf16_f32 v35, v140, v141
	s_nop 0
	v_cvt_pk_bf16_f32 v36, v142, v143
	s_nop 0
	v_cvt_pk_bf16_f32 v37, v144, v145
	ds_read_b64_tr_b16 v[38:39], v46 offset:32256
	ds_read_b64_tr_b16 v[40:41], v46 offset:33408
	ds_read_b64_tr_b16 v[42:43], v46 offset:32320
	ds_read_b64_tr_b16 v[44:45], v46 offset:33472
	s_waitcnt lgkmcnt(2)
	v_mfma_f32_32x32x16_bf16 v[18:33], v[38:41], v[34:37], v[18:33]
	s_waitcnt lgkmcnt(0)
	v_mfma_f32_32x32x16_bf16 v[2:17], v[42:45], v[34:37], v[2:17]
	s_nop 0
	v_cvt_pk_bf16_f32 v34, v146, v147
	s_nop 0
	v_cvt_pk_bf16_f32 v35, v148, v149
	s_nop 0
	v_cvt_pk_bf16_f32 v36, v150, v151
	s_nop 0
	v_cvt_pk_bf16_f32 v37, v152, v153
	ds_read_b64_tr_b16 v[38:39], v46 offset:34560
	ds_read_b64_tr_b16 v[40:41], v46 offset:35712
	ds_read_b64_tr_b16 v[42:43], v46 offset:34624
	ds_read_b64_tr_b16 v[44:45], v46 offset:35776
	s_waitcnt lgkmcnt(2)
	v_mfma_f32_32x32x16_bf16 v[18:33], v[38:41], v[34:37], v[18:33]
	s_waitcnt lgkmcnt(0)
	v_mfma_f32_32x32x16_bf16 v[2:17], v[42:45], v[34:37], v[2:17]
	s_nop 0
	v_cvt_pk_bf16_f32 v34, v154, v155
	s_nop 0
	v_cvt_pk_bf16_f32 v35, v156, v157
	s_nop 0
	v_cvt_pk_bf16_f32 v36, v158, v159
	s_nop 0
	v_cvt_pk_bf16_f32 v37, v160, v161
	ds_read_b64_tr_b16 v[38:39], v223 offset:59904
	ds_read_b64_tr_b16 v[40:41], v223 offset:61056
	ds_read_b64_tr_b16 v[42:43], v223 offset:59968
	ds_read_b64_tr_b16 v[44:45], v223 offset:61120
	s_waitcnt lgkmcnt(2)
	v_mfma_f32_32x32x16_bf16 v[18:33], v[38:41], v[34:37], v[18:33]
	s_waitcnt lgkmcnt(0)
	v_mfma_f32_32x32x16_bf16 v[2:17], v[42:45], v[34:37], v[2:17]
	s_nop 0
	v_cvt_pk_bf16_f32 v34, v162, v162
	s_nop 0
	v_cvt_pk_bf16_f32 v35, v162, v162
	s_nop 0
	v_cvt_pk_bf16_f32 v36, v162, v162
	s_nop 0
	v_cvt_pk_bf16_f32 v37, v162, v162
	ds_read_b64_tr_b16 v[38:39], v223 offset:62208
	ds_read_b64_tr_b16 v[40:41], v223 offset:63360
	ds_read_b64_tr_b16 v[42:43], v223 offset:62272
	ds_read_b64_tr_b16 v[44:45], v223 offset:63424
	s_waitcnt lgkmcnt(2)
	v_mfma_f32_32x32x16_bf16 v[18:33], v[38:41], v[34:37], v[18:33]
	s_waitcnt lgkmcnt(0)
	v_mfma_f32_32x32x16_bf16 v[2:17], v[42:45], v[34:37], v[2:17]
	v_add_f32_e32 v34, v163, v164
	v_add_f32_e32 v34, v165, v34
	v_div_scale_f32 v35, s[0:1], v34, v34, 1.0
	v_rcp_f32_e32 v36, v35
	s_nop 0
	v_fma_f32 v37, -v35, v36, 1.0
	v_fmac_f32_e32 v36, v37, v36
	v_div_scale_f32 v37, vcc, 1.0, v34, 1.0
	v_mul_f32_e32 v38, v37, v36
	v_fma_f32 v39, -v35, v38, v37
	v_fmac_f32_e32 v38, v39, v36
	v_fma_f32 v35, -v35, v38, v37
	v_div_fmas_f32 v35, v35, v36, v38
	v_div_fixup_f32 v36, v35, v34, 1.0
	v_mul_f32_e32 v36, 0x42c80000, v36
	v_mul_f32_e32 v3, v36, v3
	v_mul_f32_e32 v2, v36, v2
	v_mul_f32_e32 v4, v36, v4
	v_mul_f32_e32 v5, v36, v5
	v_med3_f32 v3, v3, s13, v227
	v_med3_f32 v2, v2, s13, v227
	v_rndne_f32_e32 v3, v3
	v_med3_f32 v4, v4, s13, v227
	v_med3_f32 v5, v5, s13, v227
	v_rndne_f32_e32 v2, v2
	v_cvt_i32_f32_e32 v3, v3
	v_rndne_f32_e32 v4, v4
	v_rndne_f32_e32 v5, v5
	v_cvt_i32_f32_e32 v2, v2
	v_cvt_i32_f32_sdwa v4, v4 dst_sel:WORD_1 dst_unused:UNUSED_PAD src0_sel:DWORD
	v_cvt_i32_f32_e32 v5, v5
	v_lshlrev_b32_e32 v3, 8, v3
	v_and_b32_e32 v3, 0xff00, v3
	v_and_b32_e32 v4, 0xff0000, v4
	v_perm_b32 v2, v5, v2, s33
	v_lshl_add_u64 v[34:35], v[214:215], 0, v[216:217]
	v_or3_b32 v2, v2, v3, v4
	v_mul_f32_e32 v3, v36, v23
	global_store_dword v[34:35], v2, off offset:32
	v_mul_f32_e32 v2, v36, v22
	v_mul_f32_e32 v4, v36, v24
	v_mul_f32_e32 v5, v36, v25
	v_med3_f32 v3, v3, s13, v227
	v_med3_f32 v2, v2, s13, v227
	v_rndne_f32_e32 v3, v3
	v_med3_f32 v4, v4, s13, v227
	v_med3_f32 v5, v5, s13, v227
	v_rndne_f32_e32 v2, v2
	v_cvt_i32_f32_e32 v3, v3
	v_rndne_f32_e32 v4, v4
	v_rndne_f32_e32 v5, v5
	v_cvt_i32_f32_e32 v2, v2
	v_cvt_i32_f32_sdwa v4, v4 dst_sel:WORD_1 dst_unused:UNUSED_PAD src0_sel:DWORD
	v_cvt_i32_f32_e32 v5, v5
	v_lshlrev_b32_e32 v3, 8, v3
	v_and_b32_e32 v3, 0xff00, v3
	v_and_b32_e32 v4, 0xff0000, v4
	v_perm_b32 v2, v5, v2, s33
	v_or3_b32 v2, v2, v3, v4
	v_mul_f32_e32 v3, v36, v7
	global_store_dword v[34:35], v2, off offset:8
	v_mul_f32_e32 v2, v36, v6
	v_mul_f32_e32 v4, v36, v8
	v_mul_f32_e32 v5, v36, v9
	v_med3_f32 v3, v3, s13, v227
	v_med3_f32 v2, v2, s13, v227
	v_rndne_f32_e32 v3, v3
	v_med3_f32 v4, v4, s13, v227
	v_med3_f32 v5, v5, s13, v227
	v_rndne_f32_e32 v2, v2
	v_cvt_i32_f32_e32 v3, v3
	v_rndne_f32_e32 v4, v4
	v_rndne_f32_e32 v5, v5
	v_cvt_i32_f32_e32 v2, v2
	v_cvt_i32_f32_sdwa v4, v4 dst_sel:WORD_1 dst_unused:UNUSED_PAD src0_sel:DWORD
	v_cvt_i32_f32_e32 v5, v5
	v_lshlrev_b32_e32 v3, 8, v3
	v_and_b32_e32 v3, 0xff00, v3
	v_and_b32_e32 v4, 0xff0000, v4
	v_perm_b32 v2, v5, v2, s33
	v_or3_b32 v2, v2, v3, v4
	v_mul_f32_e32 v3, v36, v27
	global_store_dword v[34:35], v2, off offset:40
	v_mul_f32_e32 v2, v36, v26
	v_mul_f32_e32 v4, v36, v28
	v_mul_f32_e32 v5, v36, v29
	v_med3_f32 v3, v3, s13, v227
	v_med3_f32 v2, v2, s13, v227
	v_rndne_f32_e32 v3, v3
	v_med3_f32 v4, v4, s13, v227
	v_med3_f32 v5, v5, s13, v227
	v_rndne_f32_e32 v2, v2
	v_cvt_i32_f32_e32 v3, v3
	v_rndne_f32_e32 v4, v4
	v_rndne_f32_e32 v5, v5
	v_cvt_i32_f32_e32 v2, v2
	v_cvt_i32_f32_sdwa v4, v4 dst_sel:WORD_1 dst_unused:UNUSED_PAD src0_sel:DWORD
	v_cvt_i32_f32_e32 v5, v5
	v_lshlrev_b32_e32 v3, 8, v3
	v_and_b32_e32 v3, 0xff00, v3
	v_and_b32_e32 v4, 0xff0000, v4
	v_perm_b32 v2, v5, v2, s33
	v_or3_b32 v2, v2, v3, v4
	v_mul_f32_e32 v3, v36, v11
	global_store_dword v[34:35], v2, off offset:16
	v_mul_f32_e32 v2, v36, v10
	v_mul_f32_e32 v4, v36, v12
	v_mul_f32_e32 v5, v36, v13
	v_med3_f32 v3, v3, s13, v227
	v_med3_f32 v2, v2, s13, v227
	v_rndne_f32_e32 v3, v3
	v_med3_f32 v4, v4, s13, v227
	v_med3_f32 v5, v5, s13, v227
	v_rndne_f32_e32 v2, v2
	v_cvt_i32_f32_e32 v3, v3
	v_rndne_f32_e32 v4, v4
	v_rndne_f32_e32 v5, v5
	v_cvt_i32_f32_e32 v2, v2
	v_cvt_i32_f32_sdwa v4, v4 dst_sel:WORD_1 dst_unused:UNUSED_PAD src0_sel:DWORD
	v_cvt_i32_f32_e32 v5, v5
	v_lshlrev_b32_e32 v3, 8, v3
	v_and_b32_e32 v3, 0xff00, v3
	v_and_b32_e32 v4, 0xff0000, v4
	v_perm_b32 v2, v5, v2, s33
	v_or3_b32 v2, v2, v3, v4
	v_mul_f32_e32 v3, v36, v31
	global_store_dword v[34:35], v2, off offset:48
	v_mul_f32_e32 v2, v36, v30
	v_mul_f32_e32 v4, v36, v32
	v_mul_f32_e32 v5, v36, v33
	v_med3_f32 v3, v3, s13, v227
	v_med3_f32 v2, v2, s13, v227
	v_rndne_f32_e32 v3, v3
	v_med3_f32 v4, v4, s13, v227
	v_med3_f32 v5, v5, s13, v227
	v_rndne_f32_e32 v2, v2
	v_cvt_i32_f32_e32 v3, v3
	v_rndne_f32_e32 v4, v4
	v_rndne_f32_e32 v5, v5
	v_cvt_i32_f32_e32 v2, v2
	v_cvt_i32_f32_sdwa v4, v4 dst_sel:WORD_1 dst_unused:UNUSED_PAD src0_sel:DWORD
	v_cvt_i32_f32_e32 v5, v5
	v_lshlrev_b32_e32 v3, 8, v3
	v_and_b32_e32 v3, 0xff00, v3
	v_and_b32_e32 v4, 0xff0000, v4
	v_perm_b32 v2, v5, v2, s33
	v_mul_f32_e32 v19, v36, v19
	v_or3_b32 v2, v2, v3, v4
	v_mul_f32_e32 v3, v36, v15
	v_mul_f32_e32 v18, v36, v18
	v_mul_f32_e32 v20, v36, v20
	v_mul_f32_e32 v21, v36, v21
	v_med3_f32 v19, v19, s13, v227
	global_store_dword v[34:35], v2, off offset:24
	v_mul_f32_e32 v2, v36, v14
	v_mul_f32_e32 v4, v36, v16
	v_mul_f32_e32 v5, v36, v17
	v_med3_f32 v3, v3, s13, v227
	v_med3_f32 v18, v18, s13, v227
	v_rndne_f32_e32 v19, v19
	v_med3_f32 v20, v20, s13, v227
	v_med3_f32 v21, v21, s13, v227
	v_med3_f32 v2, v2, s13, v227
	v_rndne_f32_e32 v3, v3
	v_med3_f32 v4, v4, s13, v227
	v_med3_f32 v5, v5, s13, v227
	v_rndne_f32_e32 v18, v18
	v_cvt_i32_f32_e32 v19, v19
	v_rndne_f32_e32 v20, v20
	v_rndne_f32_e32 v21, v21
	v_rndne_f32_e32 v2, v2
	v_cvt_i32_f32_e32 v3, v3
	v_rndne_f32_e32 v4, v4
	v_rndne_f32_e32 v5, v5
	v_cvt_i32_f32_e32 v18, v18
	v_cvt_i32_f32_sdwa v20, v20 dst_sel:WORD_1 dst_unused:UNUSED_PAD src0_sel:DWORD
	v_cvt_i32_f32_e32 v21, v21
	v_cvt_i32_f32_e32 v2, v2
	v_cvt_i32_f32_sdwa v4, v4 dst_sel:WORD_1 dst_unused:UNUSED_PAD src0_sel:DWORD
	v_cvt_i32_f32_e32 v5, v5
	v_lshlrev_b32_e32 v19, 8, v19
	v_lshlrev_b32_e32 v3, 8, v3
	v_and_b32_e32 v19, 0xff00, v19
	v_and_b32_e32 v20, 0xff0000, v20
	v_perm_b32 v18, v21, v18, s33
	v_and_b32_e32 v3, 0xff00, v3
	v_and_b32_e32 v4, 0xff0000, v4
	v_perm_b32 v2, v5, v2, s33
	v_or3_b32 v18, v18, v19, v20
	v_or3_b32 v2, v2, v3, v4
	s_and_b64 vcc, exec, s[16:17]
	s_mov_b32 s16, 1
	global_store_dword v[34:35], v18, off
	global_store_dword v[34:35], v2, off offset:56
	s_cbranch_vccz .LBB0_645
	v_readlane_b32 s0, v254, 60
	v_readlane_b32 s96, v254, 45
	v_readlane_b32 s1, v254, 61
	v_readlane_b32 s97, v254, 46
	s_mov_b64 s[2:3], -1
	s_and_b64 vcc, exec, s[0:1]
	v_readlane_b32 s97, v253, 28
	v_readlane_b32 s16, v254, 18
	v_readlane_b32 s60, v253, 12
	s_barrier
	v_readlane_b32 s17, v254, 19
	v_readlane_b32 s18, v254, 20
	v_readlane_b32 s19, v254, 21
	v_readlane_b32 s20, v254, 22
	v_readlane_b32 s21, v254, 23
	v_readlane_b32 s22, v254, 24
	v_readlane_b32 s23, v254, 25
	v_readlane_b32 s24, v254, 26
	v_readlane_b32 s25, v254, 27
	v_readlane_b32 s26, v254, 28
	v_readlane_b32 s27, v254, 29
	v_readlane_b32 s28, v254, 30
	v_readlane_b32 s29, v254, 31
	v_readlane_b32 s30, v254, 32
	v_readlane_b32 s31, v254, 33
	v_readlane_b32 s61, v253, 13
	s_cbranch_vccz .LBB0_627
	ds_write_b128 v233, v[106:109]
	ds_write_b128 v233, v[102:105] offset:32256
	ds_write_b128 v225, v[98:101]
	ds_write_b128 v225, v[110:113] offset:32256
	s_mov_b64 s[2:3], exec
	v_readlane_b32 s0, v253, 18
	v_readlane_b32 s1, v253, 19
	s_and_b64 s[0:1], s[2:3], s[0:1]
	s_mov_b64 exec, s[0:1]
	s_cbranch_execz .LBB0_649
	ds_write_b128 v233, v[114:117] offset:18432
	ds_write_b128 v233, v[118:121] offset:50688

	.amdhsa_kernel _Z10fwd_kernel4Args
		.amdhsa_group_segment_fixed_size 0
		.amdhsa_private_segment_fixed_size 0
		.amdhsa_kernarg_size 416
		.amdhsa_user_sgpr_count 2
		.amdhsa_user_sgpr_dispatch_ptr 0
		.amdhsa_user_sgpr_queue_ptr 0
		.amdhsa_user_sgpr_kernarg_segment_ptr 1
		.amdhsa_user_sgpr_dispatch_id 0
		.amdhsa_user_sgpr_kernarg_preload_length 0
		.amdhsa_user_sgpr_kernarg_preload_offset 0
		.amdhsa_user_sgpr_private_segment_size 0
		.amdhsa_uses_dynamic_stack 0
		.amdhsa_enable_private_segment 0
		.amdhsa_system_sgpr_workgroup_id_x 1
		.amdhsa_system_sgpr_workgroup_id_y 0
		.amdhsa_system_sgpr_workgroup_id_z 0
		.amdhsa_system_sgpr_workgroup_info 0
		.amdhsa_system_vgpr_workitem_id 0
		.amdhsa_next_free_vgpr 256
		.amdhsa_next_free_sgpr 98
		.amdhsa_accum_offset 256
		.amdhsa_reserve_vcc 1
		.amdhsa_float_round_mode_32 0
		.amdhsa_float_round_mode_16_64 0
		.amdhsa_float_denorm_mode_32 3
		.amdhsa_float_denorm_mode_16_64 3
		.amdhsa_dx10_clamp 1
		.amdhsa_ieee_mode 1
		.amdhsa_fp16_overflow 0
		.amdhsa_tg_split 0
		.amdhsa_exception_fp_ieee_invalid_op 0
		.amdhsa_exception_fp_denorm_src 0
		.amdhsa_exception_fp_ieee_div_zero 0
		.amdhsa_exception_fp_ieee_overflow 0
		.amdhsa_exception_fp_ieee_underflow 0
		.amdhsa_exception_fp_ieee_inexact 0
		.amdhsa_exception_int_div_zero 0
	.end_amdhsa_kernel

amdhsa.kernels:
  - .agpr_count:     0
    .args:
      - .offset:         0
        .size:           160
        .value_kind:     by_value
      - .offset:         160
        .size:           4
        .value_kind:     hidden_block_count_x
      - .offset:         164
        .size:           4
        .value_kind:     hidden_block_count_y
      - .offset:         168
        .size:           4
        .value_kind:     hidden_block_count_z
      - .offset:         172
        .size:           2
        .value_kind:     hidden_group_size_x
      - .offset:         174
        .size:           2
        .value_kind:     hidden_group_size_y
      - .offset:         176
        .size:           2
        .value_kind:     hidden_group_size_z
      - .offset:         178
        .size:           2
        .value_kind:     hidden_remainder_x
      - .offset:         180
        .size:           2
        .value_kind:     hidden_remainder_y
      - .offset:         182
        .size:           2
        .value_kind:     hidden_remainder_z
      - .offset:         200
        .size:           8
        .value_kind:     hidden_global_offset_x
      - .offset:         208
        .size:           8
        .value_kind:     hidden_global_offset_y
      - .offset:         216
        .size:           8
        .value_kind:     hidden_global_offset_z
      - .offset:         224
        .size:           2
        .value_kind:     hidden_grid_dims
      - .offset:         280
        .size:           4
        .value_kind:     hidden_dynamic_lds_size
    .group_segment_fixed_size: 0
    .kernarg_segment_align: 8
    .kernarg_segment_size: 416
    .language:       OpenCL C
    .language_version:
      - 2
      - 0
    .max_flat_workgroup_size: 512
    .name:           _Z10fwd_kernel4Args
    .private_segment_fixed_size: 0
    .sgpr_count:     104
    .sgpr_spill_count: 115
    .symbol:         _Z10fwd_kernel4Args.kd
    .uniform_work_group_size: 1
    .uses_dynamic_stack: false
    .vgpr_count:     256
    .vgpr_spill_count: 0
    .wavefront_size: 64
